# attention: self-max canonicalisations on the row-max chain dropped in all five step copies (main loop and tail)
# baseline (speedup 1.0000x reference)
.LBB0_1382:
	v_add_u32_e32 v0, s64, v240
	ds_read_b64_tr_b16 v[6:7], v0 offset:24576
	ds_read_b64_tr_b16 v[8:9], v0 offset:25088
	v_add_f32_e32 v2, v80, v81
	v_add_f32_e32 v2, v82, v2
	v_add_f32_e32 v2, v83, v2
	v_add_f32_e32 v2, v84, v2
	v_add_f32_e32 v10, v85, v2
	v_cvt_pk_bf16_f32 v156, v80, v81
	v_cvt_pk_bf16_f32 v157, v82, v83
	s_waitcnt lgkmcnt(3)
	v_mfma_f32_32x32x16_bf16 v[96:111], v[188:191], v[140:143], v[48:63]
	ds_read_b64_tr_b16 v[2:3], v0 offset:28672
	ds_read_b64_tr_b16 v[4:5], v0 offset:29184
	s_waitcnt lgkmcnt(4)
	v_mfma_f32_32x32x16_bf16 v[48:63], v[184:187], v[140:143], v[48:63]
	v_add_f32_e32 v10, v86, v10
	v_add_f32_e32 v10, v87, v10
	v_add_f32_e32 v10, v88, v10
	v_add_f32_e32 v14, v89, v10
	v_cvt_pk_bf16_f32 v158, v84, v85
	v_cvt_pk_bf16_f32 v159, v86, v87
	ds_read_b64_tr_b16 v[10:11], v0 offset:25600
	ds_read_b64_tr_b16 v[12:13], v0 offset:26112
	v_add_f32_e32 v14, v90, v14
	v_add_f32_e32 v14, v91, v14
	v_add_f32_e32 v14, v92, v14
	v_add_f32_e32 v14, v93, v14
	v_cvt_pk_bf16_f32 v152, v88, v89
	v_cvt_pk_bf16_f32 v153, v90, v91
	v_mfma_f32_32x32x16_bf16 v[96:111], v[180:183], v[136:139], v[96:111]
	ds_read_b64_tr_b16 v[112:113], v0 offset:29696
	ds_read_b64_tr_b16 v[114:115], v0 offset:30208
	v_mfma_f32_32x32x16_bf16 v[48:63], v[176:179], v[136:139], v[48:63]
	v_add_f32_e32 v14, v94, v14
	v_add_f32_e32 v14, v95, v14
	v_add_f32_e32 v14, v64, v14
	v_add_f32_e32 v14, v65, v14
	v_cvt_pk_bf16_f32 v154, v92, v93
	v_cvt_pk_bf16_f32 v155, v94, v95
	ds_read_b64_tr_b16 v[116:117], v0 offset:26624
	ds_read_b64_tr_b16 v[118:119], v0 offset:27136
	v_add_f32_e32 v14, v66, v14
	v_add_f32_e32 v14, v67, v14
	v_add_f32_e32 v14, v68, v14
	v_add_f32_e32 v14, v69, v14
	v_cvt_pk_bf16_f32 v148, v64, v65
	v_cvt_pk_bf16_f32 v149, v66, v67
	v_mfma_f32_32x32x16_bf16 v[96:111], v[172:175], v[132:135], v[96:111]
	ds_read_b64_tr_b16 v[120:121], v0 offset:30720
	ds_read_b64_tr_b16 v[122:123], v0 offset:31232
	v_mfma_f32_32x32x16_bf16 v[48:63], v[168:171], v[132:135], v[48:63]
	v_add_f32_e32 v14, v70, v14
	v_add_f32_e32 v14, v71, v14
	v_add_f32_e32 v14, v72, v14
	v_add_f32_e32 v14, v73, v14
	v_cvt_pk_bf16_f32 v150, v68, v69
	v_cvt_pk_bf16_f32 v151, v70, v71
	ds_read_b64_tr_b16 v[124:125], v0 offset:27648
	ds_read_b64_tr_b16 v[126:127], v0 offset:28160
	v_add_f32_e32 v14, v74, v14
	v_add_f32_e32 v14, v75, v14
	v_add_f32_e32 v14, v76, v14
	v_add_f32_e32 v14, v77, v14
	v_cvt_pk_bf16_f32 v144, v72, v73
	v_cvt_pk_bf16_f32 v145, v74, v75
	v_mfma_f32_32x32x16_bf16 v[96:111], v[164:167], v[128:131], v[96:111]
	ds_read_b64_tr_b16 v[132:133], v0 offset:31744
	ds_read_b64_tr_b16 v[134:135], v0 offset:32256
	v_mfma_f32_32x32x16_bf16 v[48:63], v[160:163], v[128:131], v[48:63]
	v_add_f32_e32 v0, v78, v14
	v_add_f32_e32 v0, v79, v0
	v_add_f32_e32 v0, 0, v0
	v_cvt_pk_bf16_f32 v146, v76, v77
	v_cvt_pk_bf16_f32 v147, v78, v79
	v_lshl_add_u32 v14, s76, 2, v225
	v_add_u32_e32 v15, 0xffffff00, v14
	v_add_u32_e32 v68, 0xffffff80, v14
	ds_read_b128 v[64:67], v15
	ds_read_b128 v[68:71], v68
	v_add_u32_e32 v15, 0xffffff20, v14
	v_add_u32_e32 v76, 0xffffffa0, v14
	ds_read_b128 v[72:75], v15
	ds_read_b128 v[76:79], v76
	v_add_u32_e32 v15, 0xffffff40, v14
	v_subrev_u32_e32 v84, 64, v14
	ds_read_b128 v[80:83], v15
	ds_read_b128 v[84:87], v84
	v_add_u32_e32 v15, 0xffffff60, v14
	v_subrev_u32_e32 v14, 32, v14
	ds_read_b128 v[88:91], v15
	ds_read_b128 v[92:95], v14
	s_waitcnt lgkmcnt(7)
	v_add_f32_e32 v14, v98, v66
	v_add_f32_e32 v15, v99, v67
	v_or_b32_e32 v67, 0xe0, v221
	s_waitcnt lgkmcnt(6)
	v_add_f32_e32 v48, v48, v68
	v_add_f32_e32 v49, v49, v69
	v_or_b32_e32 v66, 0xc0, v221
	v_cmp_le_i32_e32 vcc, v67, v227
	v_add_f32_e32 v64, v96, v64
	v_add_f32_e32 v65, v97, v65
	v_add_f32_e32 v50, v50, v70
	v_add_f32_e32 v51, v51, v71
	v_cndmask_b32_e32 v48, v238, v48, vcc
	v_cmp_lt_i32_e32 vcc, v66, v227
	s_waitcnt lgkmcnt(5)
	v_add_f32_e32 v72, v100, v72
	v_add_f32_e32 v73, v101, v73
	s_waitcnt lgkmcnt(4)
	v_add_f32_e32 v52, v52, v76
	v_add_f32_e32 v53, v53, v77
	v_cndmask_b32_e32 v65, v238, v65, vcc
	v_cmp_le_i32_e32 vcc, v66, v227
	v_or_b32_e32 v66, 0xe1, v221
	v_add_f32_e32 v74, v102, v74
	v_add_f32_e32 v75, v103, v75
	v_cndmask_b32_e32 v64, v238, v64, vcc
	v_cmp_le_i32_e32 vcc, v66, v227
	v_or_b32_e32 v66, 0xc2, v221
	v_add_f32_e32 v54, v54, v78
	v_add_f32_e32 v55, v55, v79
	v_cndmask_b32_e32 v49, v238, v49, vcc
	v_cmp_le_i32_e32 vcc, v66, v227
	s_waitcnt lgkmcnt(3)
	v_add_f32_e32 v80, v104, v80
	v_add_f32_e32 v81, v105, v81
	s_waitcnt lgkmcnt(2)
	v_add_f32_e32 v56, v56, v84
	v_add_f32_e32 v57, v57, v85
	v_cndmask_b32_e32 v66, v238, v14, vcc
	v_or_b32_e32 v14, 0xe2, v221
	v_cmp_le_i32_e32 vcc, v14, v227
	v_or_b32_e32 v14, 0xc3, v221
	v_add_f32_e32 v82, v106, v82
	v_add_f32_e32 v83, v107, v83
	v_cndmask_b32_e32 v50, v238, v50, vcc
	v_cmp_le_i32_e32 vcc, v14, v227
	v_or_b32_e32 v14, 0xe3, v221
	v_add_f32_e32 v58, v58, v86
	v_add_f32_e32 v59, v59, v87
	v_cndmask_b32_e32 v67, v238, v15, vcc
	v_cmp_le_i32_e32 vcc, v14, v227
	v_or_b32_e32 v14, 0xc8, v221
	s_waitcnt lgkmcnt(1)
	v_add_f32_e32 v88, v108, v88
	v_add_f32_e32 v89, v109, v89
	v_cndmask_b32_e32 v51, v238, v51, vcc
	v_cmp_le_i32_e32 vcc, v14, v227
	v_or_b32_e32 v14, 0xe8, v221
	s_waitcnt lgkmcnt(0)
	v_add_f32_e32 v60, v60, v92
	v_add_f32_e32 v61, v61, v93
	v_cndmask_b32_e32 v68, v238, v72, vcc
	v_cmp_le_i32_e32 vcc, v14, v227
	v_or_b32_e32 v14, 0xc9, v221
	v_add_f32_e32 v90, v110, v90
	v_add_f32_e32 v91, v111, v91
	v_cndmask_b32_e32 v52, v238, v52, vcc
	v_cmp_le_i32_e32 vcc, v14, v227
	v_or_b32_e32 v14, 0xe9, v221
	v_add_f32_e32 v62, v62, v94
	v_add_f32_e32 v63, v63, v95
	v_cndmask_b32_e32 v69, v238, v73, vcc
	v_cmp_le_i32_e32 vcc, v14, v227
	v_or_b32_e32 v14, 0xca, v221
	v_max3_f32 v15, v66, v67, v49
	v_cndmask_b32_e32 v53, v238, v53, vcc
	v_cmp_le_i32_e32 vcc, v14, v227
	v_or_b32_e32 v14, 0xea, v221
	v_add_f32_e32 v0, v241, v0
	v_cndmask_b32_e32 v70, v238, v74, vcc
	v_cmp_le_i32_e32 vcc, v14, v227
	v_or_b32_e32 v14, 0xcb, v221
	s_nop 0
	v_cndmask_b32_e32 v54, v238, v54, vcc
	v_cmp_le_i32_e32 vcc, v14, v227
	v_or_b32_e32 v14, 0xeb, v221
	s_nop 0
	v_cndmask_b32_e32 v71, v238, v75, vcc
	v_cmp_le_i32_e32 vcc, v14, v227
	v_or_b32_e32 v14, 0xd0, v221
	v_max3_f32 v15, v15, v70, v71
	v_cndmask_b32_e32 v55, v238, v55, vcc
	v_cmp_le_i32_e32 vcc, v14, v227
	v_or_b32_e32 v14, 0xf0, v221
	v_max3_f32 v15, v15, v54, v55
	v_cndmask_b32_e32 v72, v238, v80, vcc
	v_cmp_le_i32_e32 vcc, v14, v227
	v_or_b32_e32 v14, 0xd1, v221
	s_nop 0
	v_cndmask_b32_e32 v56, v238, v56, vcc
	v_cmp_le_i32_e32 vcc, v14, v227
	v_or_b32_e32 v14, 0xf1, v221
	s_nop 0
	v_cndmask_b32_e32 v73, v238, v81, vcc
	v_cmp_le_i32_e32 vcc, v14, v227
	v_or_b32_e32 v14, 0xd2, v221
	s_nop 0
	v_cndmask_b32_e32 v57, v238, v57, vcc
	v_cmp_le_i32_e32 vcc, v14, v227
	v_or_b32_e32 v14, 0xf2, v221
	s_nop 0
	v_cndmask_b32_e32 v74, v238, v82, vcc
	v_cmp_le_i32_e32 vcc, v14, v227
	v_or_b32_e32 v14, 0xd3, v221
	s_nop 0
	v_cndmask_b32_e32 v58, v238, v58, vcc
	v_cmp_le_i32_e32 vcc, v14, v227
	v_or_b32_e32 v14, 0xf3, v221
	s_nop 0
	v_cndmask_b32_e32 v75, v238, v83, vcc
	v_cmp_le_i32_e32 vcc, v14, v227
	v_or_b32_e32 v14, 0xd8, v221
	v_max3_f32 v15, v15, v74, v75
	v_cndmask_b32_e32 v59, v238, v59, vcc
	v_cmp_le_i32_e32 vcc, v14, v227
	v_or_b32_e32 v14, 0xf8, v221
	v_max3_f32 v15, v15, v58, v59
	v_cndmask_b32_e32 v76, v238, v88, vcc
	v_cmp_le_i32_e32 vcc, v14, v227
	v_or_b32_e32 v14, 0xd9, v221
	s_nop 0
	v_cndmask_b32_e32 v60, v238, v60, vcc
	v_cmp_le_i32_e32 vcc, v14, v227
	v_or_b32_e32 v14, 0xf9, v221
	s_nop 0
	v_cndmask_b32_e32 v77, v238, v89, vcc
	v_cmp_le_i32_e32 vcc, v14, v227
	v_or_b32_e32 v14, 0xda, v221
	s_nop 0
	v_cndmask_b32_e32 v61, v238, v61, vcc
	v_cmp_le_i32_e32 vcc, v14, v227
	v_or_b32_e32 v14, 0xfa, v221
	s_nop 0
	v_cndmask_b32_e32 v78, v238, v90, vcc
	v_cmp_le_i32_e32 vcc, v14, v227
	v_or_b32_e32 v14, 0xdb, v221
	s_nop 0
	v_cndmask_b32_e32 v62, v238, v62, vcc
	v_cmp_le_i32_e32 vcc, v14, v227
	v_or_b32_e32 v14, 0xfb, v221
	s_nop 0
	v_cndmask_b32_e32 v79, v238, v91, vcc
	v_cmp_le_i32_e32 vcc, v14, v227
	v_max_f32_e32 v14, v64, v65
	v_max3_f32 v14, v14, v48, v50
	v_max3_f32 v14, v14, v51, v68
	v_max3_f32 v14, v14, v69, v52
	v_max3_f32 v14, v14, v53, v72
	v_max3_f32 v14, v14, v73, v56
	v_cndmask_b32_e32 v63, v238, v63, vcc
	v_max3_f32 v14, v14, v57, v76
	v_max3_f32 v15, v15, v78, v79
	v_max3_f32 v14, v14, v77, v60
	v_max3_f32 v15, v15, v62, v63
	v_max3_f32 v14, v14, v61, v15
	v_mov_b32_e32 v15, v14
	s_nop 1
	v_permlane32_swap_b32_e32 v14, v15
	v_max_f32_e32 v14, v14, v15
	v_cmp_lt_f32_e32 vcc, s36, v14
	s_cmp_lg_u64 vcc, 0
	s_cselect_b64 s[2:3], -1, 0
	s_cbranch_vccnz .LBB0_1395
